# grid barrier: waiting workgroups watch the top-level generation word directly, per-XCD re-broadcast hop removed
# baseline (speedup 1.0000x reference)
; DI unsigned xb_ld(unsigned* p)              { return __hip_atomic_load(p, __ATOMIC_RELAXED, __HIP_MEMORY_SCOPE_AGENT); }
; DI unsigned xb_add(unsigned* p, unsigned v) { return __hip_atomic_fetch_add(p, v, __ATOMIC_RELAXED, __HIP_MEMORY_SCOPE_AGENT); }
; #define XB_SPIN(cond, bar) do { unsigned _sp = 0; while (cond) { __builtin_amdgcn_s_sleep(0); \
;     if ((++_sp & 255u) == 0u) { if (xb_ld(&(bar)[XB_TMO])) break; if (_sp > XB_SPIN_CAP) { atomicAdd(&(bar)[XB_TMO], 1u); break; } } } } while (0)
; DI void xcd_barrier(const XcdBarrier& b) {
;     ...
;     const unsigned old = xb_add(&bar[XB_XSUB(b.x)], 1u);
;     const unsigned gen = old / nloc;
;     if (old + 1u == (gen + 1u) * nloc) {
;       __builtin_amdgcn_fence(__ATOMIC_RELEASE, "agent");
;       asm volatile("s_waitcnt vmcnt(0)" ::: "memory");
;       const unsigned og = xb_add(&bar[XB_TOP], 1u);
;       const unsigned tg = og / nx;
;       if (og + 1u == (tg + 1u) * nx) xb_add(&bar[XB_TOPGEN], 1u);
;       else XB_SPIN(xb_ld(&bar[XB_TOPGEN]) == tg, bar);
;       __builtin_amdgcn_fence(__ATOMIC_ACQUIRE, "agent");
;       xb_add(&bar[XB_XGEN(b.x)], 1u);
;       asm volatile("s_waitcnt vmcnt(0)" ::: "memory");
;     } else {
;       XB_SPIN(xb_ld(&bar[XB_XGEN(b.x)]) == gen, bar);
;       __builtin_amdgcn_fence(__ATOMIC_ACQUIRE, "agent");
;       asm volatile("s_waitcnt vmcnt(0)" ::: "memory");
.LBB0_296:
	s_or_b64 exec, exec, s[8:9]
	v_cvt_f32_u32_e32 v4, v2
	s_waitcnt vmcnt(0)
	v_readfirstlane_b32 s6, v3
	v_sub_u32_e32 v3, 0, v2
	v_rcp_iflag_f32_e32 v4, v4
	v_add_u32_e32 v5, s6, v1
	v_mul_f32_e32 v4, 0x4f7ffffe, v4
	v_cvt_u32_f32_e32 v4, v4
	v_mul_lo_u32 v1, v3, v4
	v_mul_hi_u32 v1, v4, v1
	v_add_u32_e32 v1, v4, v1
	v_mul_hi_u32 v1, v5, v1
	v_mul_lo_u32 v3, v1, v2
	v_sub_u32_e32 v3, v5, v3
	v_add_u32_e32 v4, 1, v1
	v_cmp_ge_u32_e32 vcc, v3, v2
	s_nop 1
	v_cndmask_b32_e32 v1, v1, v4, vcc
	v_sub_u32_e32 v4, v3, v2
	v_cndmask_b32_e32 v3, v3, v4, vcc
	v_add_u32_e32 v4, 1, v1
	v_cmp_ge_u32_e32 vcc, v3, v2
	v_add_u32_e32 v3, 1, v5
	s_nop 0
	v_cndmask_b32_e32 v1, v1, v4, vcc
	v_mul_lo_u32 v4, v2, v1
	v_add_u32_e32 v2, v4, v2
	v_cmp_ne_u32_e32 vcc, v3, v2
	s_and_saveexec_b64 s[6:7], vcc
	s_xor_b64 s[6:7], exec, s[6:7]
	s_cbranch_execz .LBB0_310
	s_waitcnt lgkmcnt(0)
	v_mov_b32_e32 v0, 0
	s_add_u32 s10, s2, 0x3500
	s_addc_u32 s11, s3, 0
	global_load_dword v0, v0, s[10:11] sc1
	s_waitcnt vmcnt(0)
	v_cmp_eq_u32_e32 vcc, v0, v1
	s_and_saveexec_b64 s[8:9], vcc
	s_cbranch_execz .LBB0_309
	s_mov_b32 s22, 1
	s_mov_b64 s[12:13], 0
	v_mov_b32_e32 v0, 0
	s_branch .LBB0_300

; DI unsigned xb_add(unsigned* p, unsigned v) { return __hip_atomic_fetch_add(p, v, __ATOMIC_RELAXED, __HIP_MEMORY_SCOPE_AGENT); }
; DI void xcd_barrier(const XcdBarrier& b) {
;     ...
;       __builtin_amdgcn_fence(__ATOMIC_ACQUIRE, "agent");
;       xb_add(&bar[XB_XGEN(b.x)], 1u);
;       asm volatile("s_waitcnt vmcnt(0)" ::: "memory");
.LBB0_327:
	s_or_b64 exec, exec, s[2:3]
	s_mov_b64 s[2:3], exec
	v_mbcnt_lo_u32_b32 v0, s2, 0
	v_mbcnt_hi_u32_b32 v0, s3, v0
	v_cmp_eq_u32_e32 vcc, 0, v0
	s_waitcnt vmcnt(0)
	buffer_inv sc1
	s_and_saveexec_b64 s[6:7], vcc
	s_cbranch_execz .LBB0_329
	s_bcnt1_i32_b64 s2, s[2:3]
	v_mov_b32_e32 v0, 0x2000
	v_mov_b32_e32 v1, s2
.LBB0_329:
	s_or_b64 exec, exec, s[6:7]
	s_waitcnt vmcnt(0)

; DI unsigned xb_ld(unsigned* p)              { return __hip_atomic_load(p, __ATOMIC_RELAXED, __HIP_MEMORY_SCOPE_AGENT); }
; #define XB_SPIN(cond, bar) do { unsigned _sp = 0; while (cond) { __builtin_amdgcn_s_sleep(0); \
;     if ((++_sp & 255u) == 0u) { if (xb_ld(&(bar)[XB_TMO])) break; if (_sp > XB_SPIN_CAP) { atomicAdd(&(bar)[XB_TMO], 1u); break; } } } } while (0)
; DI void xcd_barrier(const XcdBarrier& b) {
;     ...
;     } else {
;       XB_SPIN(xb_ld(&bar[XB_XGEN(b.x)]) == gen, bar);
;       __builtin_amdgcn_fence(__ATOMIC_ACQUIRE, "agent");
;       asm volatile("s_waitcnt vmcnt(0)" ::: "memory");
.LBB0_521:
	s_or_b64 exec, exec, s[14:15]
	v_cvt_f32_u32_e32 v4, v2
	s_waitcnt vmcnt(0)
	v_readfirstlane_b32 s9, v3
	v_sub_u32_e32 v3, 0, v2
	v_rcp_iflag_f32_e32 v4, v4
	v_add_u32_e32 v5, s9, v1
	v_mul_f32_e32 v4, 0x4f7ffffe, v4
	v_cvt_u32_f32_e32 v4, v4
	v_mul_lo_u32 v1, v3, v4
	v_mul_hi_u32 v1, v4, v1
	v_add_u32_e32 v1, v4, v1
	v_mul_hi_u32 v1, v5, v1
	v_mul_lo_u32 v3, v1, v2
	v_sub_u32_e32 v3, v5, v3
	v_add_u32_e32 v4, 1, v1
	v_cmp_ge_u32_e32 vcc, v3, v2
	s_nop 1
	v_cndmask_b32_e32 v1, v1, v4, vcc
	v_sub_u32_e32 v4, v3, v2
	v_cndmask_b32_e32 v3, v3, v4, vcc
	v_add_u32_e32 v4, 1, v1
	v_cmp_ge_u32_e32 vcc, v3, v2
	v_add_u32_e32 v3, 1, v5
	s_nop 0
	v_cndmask_b32_e32 v1, v1, v4, vcc
	v_mul_lo_u32 v4, v2, v1
	v_add_u32_e32 v2, v4, v2
	v_cmp_ne_u32_e32 vcc, v3, v2
	s_and_saveexec_b64 s[12:13], vcc
	s_xor_b64 s[12:13], exec, s[12:13]
	s_cbranch_execz .LBB0_535
	s_waitcnt lgkmcnt(0)
	s_add_u32 s16, s4, 0x3500
	s_addc_u32 s17, s5, 0
	global_load_dword v0, v145, s[16:17] sc1
	s_waitcnt vmcnt(0)
	v_cmp_eq_u32_e32 vcc, v0, v1
	s_and_saveexec_b64 s[14:15], vcc
	s_cbranch_execz .LBB0_534
	s_mov_b32 s9, 1
	s_mov_b64 s[18:19], 0
	s_branch .LBB0_525

; DI unsigned xb_add(unsigned* p, unsigned v) { return __hip_atomic_fetch_add(p, v, __ATOMIC_RELAXED, __HIP_MEMORY_SCOPE_AGENT); }
; DI void xcd_barrier(const XcdBarrier& b) {
;     ...
;       __builtin_amdgcn_fence(__ATOMIC_ACQUIRE, "agent");
;       xb_add(&bar[XB_XGEN(b.x)], 1u);
;       asm volatile("s_waitcnt vmcnt(0)" ::: "memory");
.LBB0_552:
	s_or_b64 exec, exec, s[4:5]
	s_mov_b64 s[4:5], exec
	v_mbcnt_lo_u32_b32 v0, s4, 0
	v_mbcnt_hi_u32_b32 v0, s5, v0
	v_cmp_eq_u32_e32 vcc, 0, v0
	s_waitcnt vmcnt(0)
	buffer_inv sc1
	s_and_saveexec_b64 s[12:13], vcc
	s_cbranch_execz .LBB0_554
	s_bcnt1_i32_b64 s4, s[4:5]
	v_mov_b32_e32 v0, s4
.LBB0_554:
	s_or_b64 exec, exec, s[12:13]
	s_waitcnt vmcnt(0)

; DI unsigned xb_ld(unsigned* p)              { return __hip_atomic_load(p, __ATOMIC_RELAXED, __HIP_MEMORY_SCOPE_AGENT); }
; #define XB_SPIN(cond, bar) do { unsigned _sp = 0; while (cond) { __builtin_amdgcn_s_sleep(0); \
;     if ((++_sp & 255u) == 0u) { if (xb_ld(&(bar)[XB_TMO])) break; if (_sp > XB_SPIN_CAP) { atomicAdd(&(bar)[XB_TMO], 1u); break; } } } } while (0)
; DI void xcd_barrier(const XcdBarrier& b) {
;     ...
;     } else {
;       XB_SPIN(xb_ld(&bar[XB_XGEN(b.x)]) == gen, bar);
;       __builtin_amdgcn_fence(__ATOMIC_ACQUIRE, "agent");
;       asm volatile("s_waitcnt vmcnt(0)" ::: "memory");
.LBB0_617:
	s_or_b64 exec, exec, s[16:17]
	v_cvt_f32_u32_e32 v4, v2
	s_waitcnt vmcnt(0)
	v_readfirstlane_b32 s9, v3
	v_sub_u32_e32 v3, 0, v2
	v_rcp_iflag_f32_e32 v4, v4
	v_add_u32_e32 v5, s9, v1
	v_mul_f32_e32 v4, 0x4f7ffffe, v4
	v_cvt_u32_f32_e32 v4, v4
	v_mul_lo_u32 v1, v3, v4
	v_mul_hi_u32 v1, v4, v1
	v_add_u32_e32 v1, v4, v1
	v_mul_hi_u32 v1, v5, v1
	v_mul_lo_u32 v3, v1, v2
	v_sub_u32_e32 v3, v5, v3
	v_add_u32_e32 v4, 1, v1
	v_cmp_ge_u32_e32 vcc, v3, v2
	s_nop 1
	v_cndmask_b32_e32 v1, v1, v4, vcc
	v_sub_u32_e32 v4, v3, v2
	v_cndmask_b32_e32 v3, v3, v4, vcc
	v_add_u32_e32 v4, 1, v1
	v_cmp_ge_u32_e32 vcc, v3, v2
	v_add_u32_e32 v3, 1, v5
	s_nop 0
	v_cndmask_b32_e32 v1, v1, v4, vcc
	v_mul_lo_u32 v4, v2, v1
	v_add_u32_e32 v2, v4, v2
	v_cmp_ne_u32_e32 vcc, v3, v2
	s_and_saveexec_b64 s[14:15], vcc
	s_xor_b64 s[14:15], exec, s[14:15]
	s_cbranch_execz .LBB0_631
	s_waitcnt lgkmcnt(0)
	s_add_u32 s18, s10, 0x3500
	s_addc_u32 s19, s11, 0
	global_load_dword v0, v145, s[18:19] sc1
	s_waitcnt vmcnt(0)
	v_cmp_eq_u32_e32 vcc, v0, v1
	s_and_saveexec_b64 s[16:17], vcc
	s_cbranch_execz .LBB0_630
	s_mov_b32 s9, 1
	s_mov_b64 s[20:21], 0
	s_branch .LBB0_621

; DI unsigned xb_add(unsigned* p, unsigned v) { return __hip_atomic_fetch_add(p, v, __ATOMIC_RELAXED, __HIP_MEMORY_SCOPE_AGENT); }
; DI void xcd_barrier(const XcdBarrier& b) {
;     ...
;       __builtin_amdgcn_fence(__ATOMIC_ACQUIRE, "agent");
;       xb_add(&bar[XB_XGEN(b.x)], 1u);
;       asm volatile("s_waitcnt vmcnt(0)" ::: "memory");
.LBB0_648:
	s_or_b64 exec, exec, s[10:11]
	s_mov_b64 s[10:11], exec
	v_mbcnt_lo_u32_b32 v0, s10, 0
	v_mbcnt_hi_u32_b32 v0, s11, v0
	v_cmp_eq_u32_e32 vcc, 0, v0
	s_waitcnt vmcnt(0)
	buffer_inv sc1
	s_and_saveexec_b64 s[14:15], vcc
	s_cbranch_execz .LBB0_650
	s_bcnt1_i32_b64 s9, s[10:11]
	v_mov_b32_e32 v0, s9
.LBB0_650:
	s_or_b64 exec, exec, s[14:15]
	s_waitcnt vmcnt(0)

; DI unsigned xb_ld(unsigned* p)              { return __hip_atomic_load(p, __ATOMIC_RELAXED, __HIP_MEMORY_SCOPE_AGENT); }
; #define XB_SPIN(cond, bar) do { unsigned _sp = 0; while (cond) { __builtin_amdgcn_s_sleep(0); \
;     if ((++_sp & 255u) == 0u) { if (xb_ld(&(bar)[XB_TMO])) break; if (_sp > XB_SPIN_CAP) { atomicAdd(&(bar)[XB_TMO], 1u); break; } } } } while (0)
; DI void xcd_barrier(const XcdBarrier& b) {
;     ...
;     } else {
;       XB_SPIN(xb_ld(&bar[XB_XGEN(b.x)]) == gen, bar);
;       __builtin_amdgcn_fence(__ATOMIC_ACQUIRE, "agent");
;       asm volatile("s_waitcnt vmcnt(0)" ::: "memory");
.LBB0_1128:
	s_or_b64 exec, exec, s[12:13]
	v_cvt_f32_u32_e32 v4, v2
	s_waitcnt vmcnt(0)
	v_readfirstlane_b32 s10, v3
	v_sub_u32_e32 v3, 0, v2
	v_rcp_iflag_f32_e32 v4, v4
	v_add_u32_e32 v5, s10, v1
	v_mul_f32_e32 v4, 0x4f7ffffe, v4
	v_cvt_u32_f32_e32 v4, v4
	v_mul_lo_u32 v1, v3, v4
	v_mul_hi_u32 v1, v4, v1
	v_add_u32_e32 v1, v4, v1
	v_mul_hi_u32 v1, v5, v1
	v_mul_lo_u32 v3, v1, v2
	v_sub_u32_e32 v3, v5, v3
	v_add_u32_e32 v4, 1, v1
	v_cmp_ge_u32_e32 vcc, v3, v2
	s_nop 1
	v_cndmask_b32_e32 v1, v1, v4, vcc
	v_sub_u32_e32 v4, v3, v2
	v_cndmask_b32_e32 v3, v3, v4, vcc
	v_add_u32_e32 v4, 1, v1
	v_cmp_ge_u32_e32 vcc, v3, v2
	v_add_u32_e32 v3, 1, v5
	s_nop 0
	v_cndmask_b32_e32 v1, v1, v4, vcc
	v_mul_lo_u32 v4, v2, v1
	v_add_u32_e32 v2, v4, v2
	v_cmp_ne_u32_e32 vcc, v3, v2
	s_and_saveexec_b64 s[10:11], vcc
	s_xor_b64 s[10:11], exec, s[10:11]
	s_cbranch_execz .LBB0_1142
	s_waitcnt lgkmcnt(0)
	s_add_u32 s14, s4, 0x3500
	s_addc_u32 s15, s5, 0
	global_load_dword v0, v145, s[14:15] sc1
	s_waitcnt vmcnt(0)
	v_cmp_eq_u32_e32 vcc, v0, v1
	s_and_saveexec_b64 s[12:13], vcc
	s_cbranch_execz .LBB0_1141
	s_mov_b32 s24, 1
	s_mov_b64 s[16:17], 0
	s_branch .LBB0_1132

; DI unsigned xb_add(unsigned* p, unsigned v) { return __hip_atomic_fetch_add(p, v, __ATOMIC_RELAXED, __HIP_MEMORY_SCOPE_AGENT); }
; DI void xcd_barrier(const XcdBarrier& b) {
;     ...
;       __builtin_amdgcn_fence(__ATOMIC_ACQUIRE, "agent");
;       xb_add(&bar[XB_XGEN(b.x)], 1u);
;       asm volatile("s_waitcnt vmcnt(0)" ::: "memory");
.LBB0_1159:
	s_or_b64 exec, exec, s[4:5]
	s_mov_b64 s[4:5], exec
	v_mbcnt_lo_u32_b32 v0, s4, 0
	v_mbcnt_hi_u32_b32 v0, s5, v0
	v_cmp_eq_u32_e32 vcc, 0, v0
	s_waitcnt vmcnt(0)
	buffer_inv sc1
	s_and_saveexec_b64 s[10:11], vcc
	s_cbranch_execz .LBB0_1161
	s_bcnt1_i32_b64 s4, s[4:5]
	v_mov_b32_e32 v0, s4
.LBB0_1161:
	s_or_b64 exec, exec, s[10:11]
	s_waitcnt vmcnt(0)

; DI unsigned xb_add(unsigned* p, unsigned v) { return __hip_atomic_fetch_add(p, v, __ATOMIC_RELAXED, __HIP_MEMORY_SCOPE_AGENT); }
; DI void xcd_barrier(const XcdBarrier& b) {
;     ...
;       __builtin_amdgcn_fence(__ATOMIC_ACQUIRE, "agent");
;       xb_add(&bar[XB_XGEN(b.x)], 1u);
;       asm volatile("s_waitcnt vmcnt(0)" ::: "memory");
.LBB0_1464:
	s_or_b64 exec, exec, s[4:5]
	s_mov_b64 s[4:5], exec
	v_mbcnt_lo_u32_b32 v0, s4, 0
	v_mbcnt_hi_u32_b32 v0, s5, v0
	v_cmp_eq_u32_e32 vcc, 0, v0
	s_waitcnt vmcnt(0)
	buffer_inv sc1
	s_and_saveexec_b64 s[10:11], vcc
	s_cbranch_execz .LBB0_1466
	s_bcnt1_i32_b64 s4, s[4:5]
	v_mov_b32_e32 v0, s4
.LBB0_1466:
	s_or_b64 exec, exec, s[10:11]
	s_waitcnt vmcnt(0)

; DI unsigned xb_ld(unsigned* p)              { return __hip_atomic_load(p, __ATOMIC_RELAXED, __HIP_MEMORY_SCOPE_AGENT); }
; #define XB_SPIN(cond, bar) do { unsigned _sp = 0; while (cond) { __builtin_amdgcn_s_sleep(0); \
;     if ((++_sp & 255u) == 0u) { if (xb_ld(&(bar)[XB_TMO])) break; if (_sp > XB_SPIN_CAP) { atomicAdd(&(bar)[XB_TMO], 1u); break; } } } } while (0)
; DI void xcd_barrier(const XcdBarrier& b) {
;     ...
;     } else {
;       XB_SPIN(xb_ld(&bar[XB_XGEN(b.x)]) == gen, bar);
;       __builtin_amdgcn_fence(__ATOMIC_ACQUIRE, "agent");
;       asm volatile("s_waitcnt vmcnt(0)" ::: "memory");
.LBB0_1594:
	s_or_b64 exec, exec, s[12:13]
	v_cvt_f32_u32_e32 v4, v2
	s_waitcnt vmcnt(0)
	v_readfirstlane_b32 s9, v3
	v_sub_u32_e32 v3, 0, v2
	v_rcp_iflag_f32_e32 v4, v4
	v_add_u32_e32 v5, s9, v1
	v_mul_f32_e32 v4, 0x4f7ffffe, v4
	v_cvt_u32_f32_e32 v4, v4
	v_mul_lo_u32 v1, v3, v4
	v_mul_hi_u32 v1, v4, v1
	v_add_u32_e32 v1, v4, v1
	v_mul_hi_u32 v1, v5, v1
	v_mul_lo_u32 v3, v1, v2
	v_sub_u32_e32 v3, v5, v3
	v_add_u32_e32 v4, 1, v1
	v_cmp_ge_u32_e32 vcc, v3, v2
	s_nop 1
	v_cndmask_b32_e32 v1, v1, v4, vcc
	v_sub_u32_e32 v4, v3, v2
	v_cndmask_b32_e32 v3, v3, v4, vcc
	v_add_u32_e32 v4, 1, v1
	v_cmp_ge_u32_e32 vcc, v3, v2
	v_add_u32_e32 v3, 1, v5
	s_nop 0
	v_cndmask_b32_e32 v1, v1, v4, vcc
	v_mul_lo_u32 v4, v2, v1
	v_add_u32_e32 v2, v4, v2
	v_cmp_ne_u32_e32 vcc, v3, v2
	s_and_saveexec_b64 s[10:11], vcc
	s_xor_b64 s[10:11], exec, s[10:11]
	s_cbranch_execz .LBB0_1608
	s_waitcnt lgkmcnt(0)
	s_add_u32 s14, s4, 0x3500
	s_addc_u32 s15, s5, 0
	global_load_dword v0, v145, s[14:15] sc1
	s_waitcnt vmcnt(0)
	v_cmp_eq_u32_e32 vcc, v0, v1
	s_and_saveexec_b64 s[12:13], vcc
	s_cbranch_execz .LBB0_1607
	s_mov_b32 s9, 1
	s_mov_b64 s[16:17], 0
	s_branch .LBB0_1598

; DI unsigned xb_add(unsigned* p, unsigned v) { return __hip_atomic_fetch_add(p, v, __ATOMIC_RELAXED, __HIP_MEMORY_SCOPE_AGENT); }
; DI void xcd_barrier(const XcdBarrier& b) {
;     ...
;       __builtin_amdgcn_fence(__ATOMIC_ACQUIRE, "agent");
;       xb_add(&bar[XB_XGEN(b.x)], 1u);
;       asm volatile("s_waitcnt vmcnt(0)" ::: "memory");
.LBB0_1625:
	s_or_b64 exec, exec, s[4:5]
	s_mov_b64 s[4:5], exec
	v_mbcnt_lo_u32_b32 v0, s4, 0
	v_mbcnt_hi_u32_b32 v0, s5, v0
	v_cmp_eq_u32_e32 vcc, 0, v0
	s_waitcnt vmcnt(0)
	buffer_inv sc1
	s_and_saveexec_b64 s[10:11], vcc
	s_cbranch_execz .LBB0_1627
	s_bcnt1_i32_b64 s4, s[4:5]
	v_mov_b32_e32 v0, s4
.LBB0_1627:
	s_or_b64 exec, exec, s[10:11]
	s_waitcnt vmcnt(0)

; DI unsigned xb_add(unsigned* p, unsigned v) { return __hip_atomic_fetch_add(p, v, __ATOMIC_RELAXED, __HIP_MEMORY_SCOPE_AGENT); }
; DI void xcd_barrier(const XcdBarrier& b) {
;     ...
;       __builtin_amdgcn_fence(__ATOMIC_ACQUIRE, "agent");
;       xb_add(&bar[XB_XGEN(b.x)], 1u);
;       asm volatile("s_waitcnt vmcnt(0)" ::: "memory");
.LBB0_1786:
	s_or_b64 exec, exec, s[4:5]
	s_mov_b64 s[4:5], exec
	v_mbcnt_lo_u32_b32 v0, s4, 0
	v_mbcnt_hi_u32_b32 v0, s5, v0
	v_cmp_eq_u32_e32 vcc, 0, v0
	s_waitcnt vmcnt(0)
	buffer_inv sc1
	s_and_saveexec_b64 s[10:11], vcc
	s_cbranch_execz .LBB0_1788
	s_bcnt1_i32_b64 s4, s[4:5]
	v_mov_b32_e32 v0, s4
.LBB0_1788:
	s_or_b64 exec, exec, s[10:11]
	s_waitcnt vmcnt(0)

; DI unsigned xb_add(unsigned* p, unsigned v) { return __hip_atomic_fetch_add(p, v, __ATOMIC_RELAXED, __HIP_MEMORY_SCOPE_AGENT); }
; DI void xcd_barrier(const XcdBarrier& b) {
;     ...
;       __builtin_amdgcn_fence(__ATOMIC_ACQUIRE, "agent");
;       xb_add(&bar[XB_XGEN(b.x)], 1u);
;       asm volatile("s_waitcnt vmcnt(0)" ::: "memory");
.LBB0_1884:
	s_or_b64 exec, exec, s[4:5]
	s_mov_b64 s[4:5], exec
	v_mbcnt_lo_u32_b32 v0, s4, 0
	v_mbcnt_hi_u32_b32 v0, s5, v0
	v_cmp_eq_u32_e32 vcc, 0, v0
	s_waitcnt vmcnt(0)
	buffer_inv sc1
	s_and_saveexec_b64 s[10:11], vcc
	s_cbranch_execz .LBB0_1886
	s_bcnt1_i32_b64 s4, s[4:5]
	v_mov_b32_e32 v0, s4
.LBB0_1886:
	s_or_b64 exec, exec, s[10:11]
	s_waitcnt vmcnt(0)

; DI unsigned xb_add(unsigned* p, unsigned v) { return __hip_atomic_fetch_add(p, v, __ATOMIC_RELAXED, __HIP_MEMORY_SCOPE_AGENT); }
; DI void xcd_barrier(const XcdBarrier& b) {
;     ...
;       __builtin_amdgcn_fence(__ATOMIC_ACQUIRE, "agent");
;       xb_add(&bar[XB_XGEN(b.x)], 1u);
;       asm volatile("s_waitcnt vmcnt(0)" ::: "memory");
.LBB0_1976:
	s_bcnt1_i32_b64 s4, s[4:5]
	v_mov_b32_e32 v0, s4
	s_getpc_b64 s[98:99]

; DI unsigned xb_add(unsigned* p, unsigned v) { return __hip_atomic_fetch_add(p, v, __ATOMIC_RELAXED, __HIP_MEMORY_SCOPE_AGENT); }
; DI void xcd_barrier(const XcdBarrier& b) {
;     ...
;       __builtin_amdgcn_fence(__ATOMIC_ACQUIRE, "agent");
;       xb_add(&bar[XB_XGEN(b.x)], 1u);
;       asm volatile("s_waitcnt vmcnt(0)" ::: "memory");
.LBB0_2031:
	s_or_b64 exec, exec, s[2:3]
	s_mov_b64 s[2:3], exec
	v_mbcnt_lo_u32_b32 v0, s2, 0
	v_mbcnt_hi_u32_b32 v0, s3, v0
	v_cmp_eq_u32_e32 vcc, 0, v0
	s_waitcnt vmcnt(0)
	buffer_inv sc1
	s_and_saveexec_b64 s[6:7], vcc
	s_cbranch_execz .LBB0_2033
	s_bcnt1_i32_b64 s2, s[2:3]
	v_mov_b32_e32 v0, 0x2000
	v_mov_b32_e32 v1, s2
.LBB0_2033:
	s_or_b64 exec, exec, s[6:7]
	s_waitcnt vmcnt(0)
